# weight-conversion stores use sc1 write-through (less L2 write-back at the full barrier)
# baseline (speedup 1.0000x reference)
.LBB0_914:
	s_or_b64 exec, exec, s[66:67]
	s_lshl_b32 s66, s76, 6
	s_ashr_i32 s67, s66, 31
	v_readlane_b32 s70, v255, 9
	v_readlane_b32 s71, v255, 10
	s_add_u32 s68, s70, s68
	v_ashrrev_i32_e32 v2, 31, v0
	s_addc_u32 s69, s71, s69
	v_mul_lo_u32 v97, s65, v0
	v_mul_lo_u32 v157, s64, v2
	v_mad_u64_u32 v[2:3], s[70:71], s64, v0, 0
	v_add3_u32 v3, v3, v157, v97
	v_lshl_add_u64 v[2:3], v[2:3], 1, s[68:69]
	v_lshl_add_u64 v[2:3], s[30:31], 1, v[2:3]
	v_lshl_add_u64 v[2:3], s[66:67], 1, v[2:3]
	v_mov_b32_e32 v159, v1
	v_lshl_add_u64 v[2:3], v[2:3], 0, v[158:159]
	v_or_b32_e32 v0, s29, v169
	s_cmp_lt_i32 s25, 2
	s_mov_b64 s[70:71], -1
	global_store_dwordx4 v[2:3], v[150:153], off sc1
	s_cbranch_scc1 .LBB0_964
	s_cmp_gt_i32 s25, 2
	s_cbranch_scc0 .LBB0_917
	s_mov_b64 s[70:71], 0

.LBB0_969:
	s_or_b64 exec, exec, s[70:71]
	v_ashrrev_i32_e32 v2, 31, v0
	v_mul_lo_u32 v97, s65, v0
	v_mul_lo_u32 v157, s64, v2
	v_mad_u64_u32 v[2:3], s[70:71], s64, v0, 0
	v_add3_u32 v3, v3, v157, v97
	v_lshl_add_u64 v[2:3], v[2:3], 1, s[68:69]
	v_lshl_add_u64 v[2:3], s[30:31], 1, v[2:3]
	v_lshl_add_u64 v[2:3], s[66:67], 1, v[2:3]
	v_mov_b32_e32 v159, v1
	v_lshl_add_u64 v[2:3], v[2:3], 0, v[158:159]
	v_or_b32_e32 v0, s29, v172
	s_cmp_lt_i32 s25, 2
	s_mov_b64 s[70:71], -1
	global_store_dwordx4 v[2:3], v[150:153], off sc1
	s_cbranch_scc1 .LBB0_1022
	s_cmp_gt_i32 s25, 2
	s_cbranch_scc0 .LBB0_972
	s_mov_b64 s[70:71], 0

.LBB0_1027:
	s_or_b64 exec, exec, s[70:71]
	v_ashrrev_i32_e32 v2, 31, v0
	v_mul_lo_u32 v97, s65, v0
	v_mul_lo_u32 v157, s64, v2
	v_mad_u64_u32 v[2:3], s[70:71], s64, v0, 0
	v_add3_u32 v3, v3, v157, v97
	v_lshl_add_u64 v[2:3], v[2:3], 1, s[68:69]
	v_lshl_add_u64 v[2:3], s[30:31], 1, v[2:3]
	v_lshl_add_u64 v[2:3], s[66:67], 1, v[2:3]
	v_mov_b32_e32 v159, v1
	v_lshl_add_u64 v[2:3], v[2:3], 0, v[158:159]
	v_or_b32_e32 v0, s29, v174
	s_cmp_lt_i32 s25, 2
	s_mov_b64 s[70:71], -1
	global_store_dwordx4 v[2:3], v[150:153], off sc1
	s_cbranch_scc1 .LBB0_1078
	s_cmp_gt_i32 s25, 2
	s_cbranch_scc0 .LBB0_1030
	s_mov_b64 s[70:71], 0

.LBB0_1083:
	s_or_b64 exec, exec, s[70:71]
	v_ashrrev_i32_e32 v2, 31, v0
	v_mul_lo_u32 v97, s65, v0
	v_mul_lo_u32 v157, s64, v2
	v_mad_u64_u32 v[2:3], s[70:71], s64, v0, 0
	v_add3_u32 v3, v3, v157, v97
	v_lshl_add_u64 v[2:3], v[2:3], 1, s[68:69]
	v_lshl_add_u64 v[2:3], s[30:31], 1, v[2:3]
	v_lshl_add_u64 v[2:3], s[66:67], 1, v[2:3]
	v_mov_b32_e32 v159, v1
	v_lshl_add_u64 v[2:3], v[2:3], 0, v[158:159]
	v_or_b32_e32 v0, s29, v176
	s_cmp_lt_i32 s25, 2
	s_mov_b64 s[70:71], -1
	global_store_dwordx4 v[2:3], v[150:153], off sc1
	s_cbranch_scc1 .LBB0_1134
	s_cmp_gt_i32 s25, 2
	s_cbranch_scc0 .LBB0_1086
	v_and_b32_e32 v2, 0xffffffe0, v0
	v_subrev_u32_e32 v3, s29, v167
	v_add_u32_e32 v2, v3, v2
	s_mov_b64 s[70:71], 0

.LBB0_1139:
	s_or_b64 exec, exec, s[70:71]
	v_ashrrev_i32_e32 v2, 31, v0
	v_mul_lo_u32 v97, s65, v0
	v_mul_lo_u32 v157, s64, v2
	v_mad_u64_u32 v[2:3], s[70:71], s64, v0, 0
	v_add3_u32 v3, v3, v157, v97
	v_lshl_add_u64 v[2:3], v[2:3], 1, s[68:69]
	v_lshl_add_u64 v[2:3], s[30:31], 1, v[2:3]
	v_lshl_add_u64 v[2:3], s[66:67], 1, v[2:3]
	v_mov_b32_e32 v159, v1
	v_lshl_add_u64 v[2:3], v[2:3], 0, v[158:159]
	v_or_b32_e32 v0, s29, v177
	s_cmp_lt_i32 s25, 2
	s_mov_b64 s[70:71], -1
	global_store_dwordx4 v[2:3], v[150:153], off sc1
	s_cbranch_scc1 .LBB0_1190
	s_cmp_gt_i32 s25, 2
	s_cbranch_scc0 .LBB0_1142
	v_and_b32_e32 v2, 0xffffffe0, v0
	v_subrev_u32_e32 v3, s29, v179
	v_add_u32_e32 v2, v3, v2
	s_mov_b64 s[70:71], 0

.LBB0_1195:
	s_or_b64 exec, exec, s[70:71]
	v_ashrrev_i32_e32 v2, 31, v0
	v_mul_lo_u32 v97, s65, v0
	v_mul_lo_u32 v157, s64, v2
	v_mad_u64_u32 v[2:3], s[70:71], s64, v0, 0
	v_add3_u32 v3, v3, v157, v97
	v_lshl_add_u64 v[2:3], v[2:3], 1, s[68:69]
	v_lshl_add_u64 v[2:3], s[30:31], 1, v[2:3]
	v_lshl_add_u64 v[2:3], s[66:67], 1, v[2:3]
	v_mov_b32_e32 v159, v1
	v_lshl_add_u64 v[2:3], v[2:3], 0, v[158:159]
	v_or_b32_e32 v0, s29, v180
	s_cmp_lt_i32 s25, 2
	s_mov_b64 s[70:71], -1
	global_store_dwordx4 v[2:3], v[150:153], off sc1
	s_cbranch_scc1 .LBB0_1243
	s_cmp_gt_i32 s25, 2
	s_cbranch_scc0 .LBB0_1198
	v_and_b32_e32 v2, 0xffffffe0, v0
	v_subrev_u32_e32 v3, s29, v173
	v_add_u32_e32 v2, v3, v2
	s_mov_b64 s[70:71], 0

.LBB0_1248:
	s_or_b64 exec, exec, s[70:71]
	v_ashrrev_i32_e32 v2, 31, v0
	v_mul_lo_u32 v97, s65, v0
	v_mul_lo_u32 v157, s64, v2
	v_mad_u64_u32 v[2:3], s[70:71], s64, v0, 0
	v_add3_u32 v3, v3, v157, v97
	v_lshl_add_u64 v[2:3], v[2:3], 1, s[68:69]
	v_lshl_add_u64 v[2:3], s[30:31], 1, v[2:3]
	v_lshl_add_u64 v[2:3], s[66:67], 1, v[2:3]
	v_mov_b32_e32 v159, v1
	v_lshl_add_u64 v[2:3], v[2:3], 0, v[158:159]
	v_or_b32_e32 v0, s29, v181
	s_cmp_lt_i32 s25, 2
	s_mov_b64 s[70:71], -1
	global_store_dwordx4 v[2:3], v[150:153], off sc1
	s_cbranch_scc1 .LBB0_1296
	s_cmp_gt_i32 s25, 2
	s_cbranch_scc0 .LBB0_1251
	v_and_b32_e32 v2, 0xffffffe0, v0
	v_subrev_u32_e32 v3, s29, v182
	v_add_u32_e32 v2, v3, v2
	s_mov_b64 s[70:71], 0

.LBB0_1301:
	s_or_b64 exec, exec, s[70:71]
	v_ashrrev_i32_e32 v2, 31, v0
	v_mul_lo_u32 v97, s65, v0
	v_mul_lo_u32 v157, s64, v2
	v_mad_u64_u32 v[2:3], s[28:29], s64, v0, 0
	v_add3_u32 v3, v3, v157, v97
	v_lshl_add_u64 v[2:3], v[2:3], 1, s[68:69]
	v_lshl_add_u64 v[2:3], s[30:31], 1, v[2:3]
	v_lshl_add_u64 v[2:3], s[66:67], 1, v[2:3]
	v_mov_b32_e32 v159, v1
	v_lshl_add_u64 v[2:3], v[2:3], 0, v[158:159]
	global_store_dwordx4 v[2:3], v[150:153], off sc1
	s_waitcnt lgkmcnt(0)
	s_andn2_b64 vcc, exec, s[62:63]
	s_cbranch_vccnz .LBB0_690
	s_waitcnt vmcnt(23)
	v_mov_b64_e32 v[12:13], v[84:85]
	s_waitcnt vmcnt(22)
	v_mov_b64_e32 v[16:17], v[88:89]
	s_waitcnt vmcnt(21)
	v_mov_b64_e32 v[20:21], v[98:99]
	s_waitcnt vmcnt(20)
	v_mov_b64_e32 v[24:25], v[92:93]
	s_waitcnt vmcnt(19)
	v_mov_b64_e32 v[28:29], v[106:107]
	s_waitcnt vmcnt(18)
	v_mov_b64_e32 v[32:33], v[102:103]
	s_waitcnt vmcnt(17)
	v_mov_b64_e32 v[36:37], v[114:115]
	s_waitcnt vmcnt(16)
	v_mov_b64_e32 v[40:41], v[110:111]
	s_waitcnt vmcnt(15)
	v_mov_b64_e32 v[44:45], v[122:123]
	s_waitcnt vmcnt(14)
	v_mov_b64_e32 v[48:49], v[118:119]
	s_waitcnt vmcnt(13)
	v_mov_b64_e32 v[52:53], v[130:131]
	s_waitcnt vmcnt(12)
	v_mov_b64_e32 v[56:57], v[126:127]
	s_waitcnt vmcnt(11)
	v_mov_b64_e32 v[60:61], v[138:139]
	s_waitcnt vmcnt(10)
	v_mov_b64_e32 v[64:65], v[134:135]
	s_waitcnt vmcnt(9)
	v_mov_b64_e32 v[68:69], v[146:147]
	s_waitcnt vmcnt(8)
	v_mov_b64_e32 v[72:73], v[142:143]
	v_mov_b64_e32 v[8:9], v[80:81]
	v_mov_b64_e32 v[4:5], v[76:77]
	v_mov_b64_e32 v[14:15], v[86:87]
	v_mov_b64_e32 v[18:19], v[90:91]
	v_mov_b64_e32 v[22:23], v[100:101]
	v_mov_b64_e32 v[26:27], v[94:95]
	v_mov_b64_e32 v[30:31], v[108:109]
	v_mov_b64_e32 v[34:35], v[104:105]
	v_mov_b64_e32 v[38:39], v[116:117]
	v_mov_b64_e32 v[42:43], v[112:113]
	v_mov_b64_e32 v[46:47], v[124:125]
	v_mov_b64_e32 v[50:51], v[120:121]
	v_mov_b64_e32 v[54:55], v[132:133]
	v_mov_b64_e32 v[58:59], v[128:129]
	v_mov_b64_e32 v[62:63], v[140:141]
	v_mov_b64_e32 v[66:67], v[136:137]
	v_mov_b64_e32 v[70:71], v[148:149]
	v_mov_b64_e32 v[74:75], v[144:145]
	v_mov_b64_e32 v[10:11], v[82:83]
	v_mov_b64_e32 v[6:7], v[78:79]
	s_branch .LBB0_690
